# half-tile GEMM K-loops: same address-add reduction (9 instead of 22 adds/iteration), nop folding, hoisted tail M0 offsets, duplicate waits dropped
# speedup vs baseline: 1.0240x; 1.0006x over previous
.LBB0_107:
	s_or_b64 exec, exec, s[72:73]
	v_mov_b32_e32 v3, v1
	s_waitcnt vmcnt(8)
	v_lshl_add_u64 v[14:15], s[0:1], 0, v[2:3]
	v_lshl_add_u64 v[18:19], s[12:13], 0, v[2:3]
	v_lshl_add_u64 v[22:23], s[14:15], 0, v[2:3]
	v_lshl_add_u64 v[66:67], s[16:17], 0, v[2:3]
	v_and_b32_e32 v84, 15, v82
	v_bfe_u32 v86, v82, 4, 2
	v_lshlrev_b32_e32 v3, 2, v82
	v_add_u32_e32 v95, 0x18000, v87
	v_lshl_add_u64 v[12:13], s[0:1], 0, v[0:1]
	v_lshl_add_u64 v[16:17], s[12:13], 0, v[0:1]
	v_lshl_add_u64 v[20:21], s[14:15], 0, v[0:1]
	v_lshl_add_u64 v[68:69], s[16:17], 0, v[0:1]
	v_lshlrev_b32_e32 v0, 6, v84
	v_lshlrev_b32_e32 v2, 4, v86
	v_and_b32_e32 v3, 32, v3
	s_mov_b64 s[12:13], 0x80
	v_readfirstlane_b32 s1, v95
	v_add_u32_e32 v96, 0x1a000, v87
	v_bitop3_b32 v24, v2, v3, v0 bitop3:0x36
	v_lshl_add_u64 v[2:3], v[12:13], 0, s[12:13]
	s_mov_b32 m0, s1
	v_readfirstlane_b32 s1, v96
	v_add_u32_e32 v97, 0x8000, v87
	s_waitcnt vmcnt(4)
	s_barrier
	global_load_lds_dwordx4 v[2:3], off
	v_lshl_add_u64 v[2:3], v[14:15], 0, s[12:13]
	s_mov_b32 m0, s1
	v_readfirstlane_b32 s1, v97
	v_add_u32_e32 v98, 0xa000, v87
	global_load_lds_dwordx4 v[2:3], off
	v_lshl_add_u64 v[2:3], v[16:17], 0, s[12:13]
	s_mov_b32 m0, s1
	v_readfirstlane_b32 s1, v98
	v_add_u32_e32 v100, 0x1c000, v87
	global_load_lds_dwordx4 v[2:3], off
	v_lshl_add_u64 v[2:3], v[18:19], 0, s[12:13]
	s_mov_b32 m0, s1
	v_readfirstlane_b32 s1, v100
	v_add_u32_e32 v101, 0x1e000, v87
	global_load_lds_dwordx4 v[2:3], off
	v_lshl_add_u64 v[2:3], v[20:21], 0, s[12:13]
	s_mov_b32 m0, s1
	v_readfirstlane_b32 s1, v101
	global_load_lds_dwordx4 v[2:3], off
	v_lshl_add_u64 v[2:3], v[22:23], 0, s[12:13]
	s_mov_b32 m0, s1
	s_sub_i32 s5, s56, s54
	global_load_lds_dwordx4 v[2:3], off
	s_sub_i32 s5, s5, s77
	s_sext_i32_i16 s5, s5
	s_lshl_b32 s1, s76, 10
	s_lshl_b32 s5, s5, 8
	s_and_b32 s0, s52, 0x80
	s_add_i32 s1, s1, s5
	s_or_b32 s0, s0, s1
	s_ashr_i32 s1, s0, 31
	s_lshl_b64 s[12:13], s[0:1], 12
	s_add_u32 s12, s57, s12
	v_readlane_b32 s36, v253, 33
	s_addc_u32 s13, s63, s13
	v_readlane_b32 s48, v253, 45
	v_readlane_b32 s49, v253, 46
	s_add_u32 s10, s48, s10
	v_lshlrev_b32_e32 v2, 14, v7
	s_addc_u32 s11, s49, s11
	s_addk_i32 s0, 0x80
	v_lshlrev_b32_e32 v0, 14, v4
	v_and_b32_e32 v2, 0x7fff8000, v2
	s_ashr_i32 s1, s0, 31
	v_and_b32_e32 v0, 0x7fff8000, v0
	v_lshl_add_u32 v2, v9, 11, v2
	s_lshl_b64 s[0:1], s[0:1], 12
	v_lshl_add_u32 v0, v5, 11, v0
	v_or_b32_e32 v2, v2, v10
	s_add_u32 s0, s57, s0
	v_bfe_u32 v85, v82, 6, 2
	s_waitcnt vmcnt(6)
	v_or_b32_e32 v0, v0, v6
	v_add_lshl_u32 v2, v2, v11, 1
	v_mov_b32_e32 v3, v1
	s_addc_u32 s1, s63, s1
	v_lshlrev_b32_e32 v25, 13, v83
	v_lshl_or_b32 v26, v85, 12, v212
	v_add_lshl_u32 v0, v0, v8, 1
	v_lshl_add_u64 v[72:73], s[12:13], 0, v[2:3]
	v_lshl_add_u64 v[76:77], s[10:11], 0, v[2:3]
	v_lshl_add_u64 v[80:81], s[0:1], 0, v[2:3]
	v_mov_b32_e32 v2, 0
	v_lshl_add_u64 v[70:71], s[12:13], 0, v[0:1]
	v_lshl_add_u64 v[74:75], s[10:11], 0, v[0:1]
	v_lshl_add_u64 v[78:79], s[0:1], 0, v[0:1]
	s_mov_b32 s0, -2
	s_mov_b64 s[10:11], 0
	v_add_u32_e32 v99, v26, v24
	v_add_u32_e32 v0, v25, v24
	v_mov_b32_e32 v3, v2
	v_mov_b32_e32 v4, v2
	v_mov_b32_e32 v5, v2
	v_mov_b32_e32 v6, v2
	v_mov_b32_e32 v7, v2
	v_mov_b32_e32 v8, v2
	v_mov_b32_e32 v9, v2
	v_mov_b32_e32 v10, v2
	v_mov_b32_e32 v11, v2
	v_mov_b32_e32 v12, v2
	v_mov_b32_e32 v13, v2
	v_mov_b32_e32 v14, v2
	v_mov_b32_e32 v15, v2
	v_mov_b32_e32 v16, v2
	v_mov_b32_e32 v17, v2
	v_mov_b32_e32 v18, v2
	v_mov_b32_e32 v19, v2
	v_mov_b32_e32 v20, v2
	v_mov_b32_e32 v21, v2
	v_mov_b32_e32 v22, v2
	v_mov_b32_e32 v23, v2
	v_mov_b32_e32 v24, v2
	v_mov_b32_e32 v25, v2
	v_mov_b32_e32 v26, v2
	v_mov_b32_e32 v27, v2
	v_mov_b32_e32 v28, v2
	v_mov_b32_e32 v29, v2
	v_mov_b32_e32 v34, v2
	v_mov_b32_e32 v35, v2
	v_mov_b32_e32 v36, v2
	v_mov_b32_e32 v37, v2
	v_mov_b32_e32 v38, v2
	v_mov_b32_e32 v39, v2
	v_mov_b32_e32 v40, v2
	v_mov_b32_e32 v41, v2
	v_mov_b32_e32 v42, v2
	v_mov_b32_e32 v43, v2
	v_mov_b32_e32 v44, v2
	v_mov_b32_e32 v45, v2
	v_mov_b32_e32 v46, v2
	v_mov_b32_e32 v47, v2
	v_mov_b32_e32 v48, v2
	v_mov_b32_e32 v49, v2
	v_mov_b32_e32 v50, v2
	v_mov_b32_e32 v51, v2
	v_mov_b32_e32 v52, v2
	v_mov_b32_e32 v53, v2
	v_mov_b32_e32 v54, v2
	v_mov_b32_e32 v55, v2
	v_mov_b32_e32 v56, v2
	v_mov_b32_e32 v57, v2
	v_mov_b32_e32 v58, v2
	v_mov_b32_e32 v59, v2
	v_mov_b32_e32 v60, v2
	v_mov_b32_e32 v61, v2
	v_mov_b32_e32 v62, v2
	v_mov_b32_e32 v63, v2
	v_mov_b32_e32 v64, v2
	v_mov_b32_e32 v65, v2
	v_mov_b32_e32 v30, v2
	v_mov_b32_e32 v31, v2
	v_mov_b32_e32 v32, v2
	v_mov_b32_e32 v33, v2
	s_barrier
	v_readlane_b32 s37, v253, 34
	v_readlane_b32 s38, v253, 35
	v_readlane_b32 s39, v253, 36
	v_readlane_b32 s40, v253, 37
	v_readlane_b32 s41, v253, 38
	v_readlane_b32 s42, v253, 39
	v_readlane_b32 s43, v253, 40
	v_readlane_b32 s44, v253, 41
	v_readlane_b32 s45, v253, 42
	v_readlane_b32 s46, v253, 43
	v_readlane_b32 s47, v253, 44
	v_readlane_b32 s50, v253, 47
	v_readlane_b32 s51, v253, 48
	v_add_u32_e32 v102, 0xc000, v87
	v_add_u32_e32 v103, 0xe000, v87
	v_readfirstlane_b32 s1, v87
	s_nop 1
.LBB0_108:
	ds_read_b128 v[104:107], v99
	ds_read_b128 v[108:111], v99 offset:1024
	ds_read_b128 v[112:115], v99 offset:2048
	ds_read_b128 v[116:119], v99 offset:3072
	v_lshl_add_u64 v[152:153], v[74:75], 0, s[10:11]
	v_lshl_add_u64 v[164:165], v[152:153], 0, s[60:61]
	s_add_i32 m0, s1, 0xc000
	ds_read_b128 v[120:123], v0
	ds_read_b128 v[124:127], v0 offset:1024
	ds_read_b128 v[128:131], v0 offset:2048
	ds_read_b128 v[132:135], v0 offset:3072
	ds_read_b128 v[136:139], v0 offset:4096
	ds_read_b128 v[140:143], v0 offset:5120
	ds_read_b128 v[144:147], v0 offset:6144
	ds_read_b128 v[148:151], v0 offset:7168
	global_load_lds_dwordx4 v[164:165], off
	v_lshl_add_u64 v[154:155], v[76:77], 0, s[10:11]
	s_add_i32 m0, s1, 0xe000
	v_lshl_add_u64 v[88:89], v[154:155], 0, s[60:61]
	global_load_lds_dwordx4 v[88:89], off
	s_waitcnt lgkmcnt(8)
	s_barrier
	s_waitcnt lgkmcnt(0)
	s_setprio 1
	v_mfma_f32_16x16x32_bf16 v[62:65], v[104:107], v[120:123], v[62:65]
	v_mfma_f32_16x16x32_bf16 v[58:61], v[112:115], v[120:123], v[58:61]
	v_mfma_f32_16x16x32_bf16 v[54:57], v[104:107], v[128:131], v[54:57]
	v_mfma_f32_16x16x32_bf16 v[50:53], v[112:115], v[128:131], v[50:53]
	v_mfma_f32_16x16x32_bf16 v[46:49], v[104:107], v[136:139], v[46:49]
	v_mfma_f32_16x16x32_bf16 v[42:45], v[112:115], v[136:139], v[42:45]
	v_mfma_f32_16x16x32_bf16 v[38:41], v[104:107], v[144:147], v[38:41]
	v_mfma_f32_16x16x32_bf16 v[34:37], v[112:115], v[144:147], v[34:37]
	v_mfma_f32_16x16x32_bf16 v[62:65], v[108:111], v[124:127], v[62:65]
	v_mfma_f32_16x16x32_bf16 v[58:61], v[116:119], v[124:127], v[58:61]
	v_mfma_f32_16x16x32_bf16 v[54:57], v[108:111], v[132:135], v[54:57]
	v_mfma_f32_16x16x32_bf16 v[50:53], v[116:119], v[132:135], v[50:53]
	v_mfma_f32_16x16x32_bf16 v[46:49], v[108:111], v[140:143], v[46:49]
	v_mfma_f32_16x16x32_bf16 v[42:45], v[116:119], v[140:143], v[42:45]
	v_mfma_f32_16x16x32_bf16 v[38:41], v[108:111], v[148:151], v[38:41]
	v_mfma_f32_16x16x32_bf16 v[34:37], v[116:119], v[148:151], v[34:37]
	s_setprio 0
	s_barrier
	v_lshl_add_u64 v[156:157], v[70:71], 0, s[10:11]
	s_add_i32 m0, s1, 0xff00
	s_nop 0
	global_load_lds_dwordx4 v[156:157], off offset:256
	s_add_i32 m0, s1, 0x11f00
	v_lshl_add_u64 v[158:159], v[72:73], 0, s[10:11]
	global_load_lds_dwordx4 v[158:159], off offset:256
	v_lshl_add_u64 v[90:91], v[152:153], 0, s[74:75]
	s_mov_b32 m0, s1
	s_barrier
	s_waitcnt lgkmcnt(0)
	s_barrier
	ds_read_b128 v[120:123], v0 offset:16384
	ds_read_b128 v[124:127], v0 offset:17408
	ds_read_b128 v[128:131], v0 offset:18432
	ds_read_b128 v[132:135], v0 offset:19456
	ds_read_b128 v[136:139], v0 offset:20480
	ds_read_b128 v[140:143], v0 offset:21504
	ds_read_b128 v[144:147], v0 offset:22528
	ds_read_b128 v[148:151], v0 offset:23552
	global_load_lds_dwordx4 v[90:91], off
	s_add_i32 m0, s1, 0x1f00
	s_nop 0
	global_load_lds_dwordx4 v[154:155], off offset:256
	s_barrier
	s_waitcnt lgkmcnt(0)
	s_setprio 1
	v_mfma_f32_16x16x32_bf16 v[2:5], v[104:107], v[120:123], v[2:5]
	v_mfma_f32_16x16x32_bf16 v[6:9], v[112:115], v[120:123], v[6:9]
	v_mfma_f32_16x16x32_bf16 v[10:13], v[104:107], v[128:131], v[10:13]
	v_mfma_f32_16x16x32_bf16 v[14:17], v[112:115], v[128:131], v[14:17]
	v_mfma_f32_16x16x32_bf16 v[18:21], v[104:107], v[136:139], v[18:21]
	v_mfma_f32_16x16x32_bf16 v[22:25], v[112:115], v[136:139], v[22:25]
	v_mfma_f32_16x16x32_bf16 v[26:29], v[104:107], v[144:147], v[26:29]
	v_mfma_f32_16x16x32_bf16 v[30:33], v[112:115], v[144:147], v[30:33]
	v_mfma_f32_16x16x32_bf16 v[2:5], v[108:111], v[124:127], v[2:5]
	v_mfma_f32_16x16x32_bf16 v[6:9], v[116:119], v[124:127], v[6:9]
	v_mfma_f32_16x16x32_bf16 v[10:13], v[108:111], v[132:135], v[10:13]
	v_mfma_f32_16x16x32_bf16 v[14:17], v[116:119], v[132:135], v[14:17]
	v_mfma_f32_16x16x32_bf16 v[18:21], v[108:111], v[140:143], v[18:21]
	v_mfma_f32_16x16x32_bf16 v[22:25], v[116:119], v[140:143], v[22:25]
	v_mfma_f32_16x16x32_bf16 v[26:29], v[108:111], v[148:151], v[26:29]
	v_mfma_f32_16x16x32_bf16 v[30:33], v[116:119], v[148:151], v[30:33]
	s_setprio 0
	s_barrier
	v_lshl_add_u64 v[160:161], v[78:79], 0, s[10:11]
	s_add_i32 m0, s1, 0x13f00
	s_nop 0
	global_load_lds_dwordx4 v[160:161], off offset:256
	s_add_i32 m0, s1, 0x15f00
	v_lshl_add_u64 v[162:163], v[80:81], 0, s[10:11]
	global_load_lds_dwordx4 v[162:163], off offset:256
	s_waitcnt vmcnt(6)
	s_barrier
	s_barrier
	ds_read_b128 v[104:107], v99 offset:32768
	ds_read_b128 v[108:111], v99 offset:33792
	ds_read_b128 v[112:115], v99 offset:34816
	ds_read_b128 v[116:119], v99 offset:35840
	s_add_i32 m0, s1, 0x3f80
	ds_read_b128 v[120:123], v0 offset:32768
	ds_read_b128 v[124:127], v0 offset:33792
	ds_read_b128 v[128:131], v0 offset:34816
	ds_read_b128 v[132:135], v0 offset:35840
	ds_read_b128 v[136:139], v0 offset:36864
	ds_read_b128 v[140:143], v0 offset:37888
	ds_read_b128 v[144:147], v0 offset:38912
	ds_read_b128 v[148:151], v0 offset:39936
	global_load_lds_dwordx4 v[164:165], off offset:128
	s_add_i32 m0, s1, 0x5f80
	s_nop 0
	global_load_lds_dwordx4 v[88:89], off offset:128
	s_waitcnt lgkmcnt(8)
	s_barrier
	s_waitcnt lgkmcnt(0)
	s_setprio 1
	v_mfma_f32_16x16x32_bf16 v[62:65], v[104:107], v[120:123], v[62:65]
	v_mfma_f32_16x16x32_bf16 v[58:61], v[112:115], v[120:123], v[58:61]
	v_mfma_f32_16x16x32_bf16 v[54:57], v[104:107], v[128:131], v[54:57]
	v_mfma_f32_16x16x32_bf16 v[50:53], v[112:115], v[128:131], v[50:53]
	v_mfma_f32_16x16x32_bf16 v[46:49], v[104:107], v[136:139], v[46:49]
	v_mfma_f32_16x16x32_bf16 v[42:45], v[112:115], v[136:139], v[42:45]
	v_mfma_f32_16x16x32_bf16 v[38:41], v[104:107], v[144:147], v[38:41]
	v_mfma_f32_16x16x32_bf16 v[34:37], v[112:115], v[144:147], v[34:37]
	v_mfma_f32_16x16x32_bf16 v[62:65], v[108:111], v[124:127], v[62:65]
	v_mfma_f32_16x16x32_bf16 v[58:61], v[116:119], v[124:127], v[58:61]
	v_mfma_f32_16x16x32_bf16 v[54:57], v[108:111], v[132:135], v[54:57]
	v_mfma_f32_16x16x32_bf16 v[50:53], v[116:119], v[132:135], v[50:53]
	v_mfma_f32_16x16x32_bf16 v[46:49], v[108:111], v[140:143], v[46:49]
	v_mfma_f32_16x16x32_bf16 v[42:45], v[116:119], v[140:143], v[42:45]
	v_mfma_f32_16x16x32_bf16 v[38:41], v[108:111], v[148:151], v[38:41]
	v_mfma_f32_16x16x32_bf16 v[34:37], v[116:119], v[148:151], v[34:37]
	s_setprio 0
	s_barrier
	s_add_i32 m0, s1, 0x17e80
	s_nop 0
	global_load_lds_dwordx4 v[156:157], off offset:384
	s_add_i32 m0, s1, 0x19e80
	s_nop 0
	global_load_lds_dwordx4 v[158:159], off offset:384
	s_add_i32 m0, s1, 0x7e80
	s_barrier
	s_waitcnt lgkmcnt(0)
	s_barrier
	ds_read_b128 v[120:123], v0 offset:49152
	ds_read_b128 v[124:127], v0 offset:50176
	ds_read_b128 v[128:131], v0 offset:51200
	ds_read_b128 v[132:135], v0 offset:52224
	ds_read_b128 v[136:139], v0 offset:53248
	ds_read_b128 v[140:143], v0 offset:54272
	ds_read_b128 v[144:147], v0 offset:55296
	ds_read_b128 v[148:151], v0 offset:56320
	global_load_lds_dwordx4 v[152:153], off offset:384
	s_add_i32 m0, s1, 0x9e80
	s_nop 0
	global_load_lds_dwordx4 v[154:155], off offset:384
	s_barrier
	s_waitcnt lgkmcnt(0)
	s_setprio 1
	v_mfma_f32_16x16x32_bf16 v[2:5], v[104:107], v[120:123], v[2:5]
	v_mfma_f32_16x16x32_bf16 v[6:9], v[112:115], v[120:123], v[6:9]
	v_mfma_f32_16x16x32_bf16 v[10:13], v[104:107], v[128:131], v[10:13]
	v_mfma_f32_16x16x32_bf16 v[14:17], v[112:115], v[128:131], v[14:17]
	v_mfma_f32_16x16x32_bf16 v[18:21], v[104:107], v[136:139], v[18:21]
	v_mfma_f32_16x16x32_bf16 v[22:25], v[112:115], v[136:139], v[22:25]
	v_mfma_f32_16x16x32_bf16 v[26:29], v[104:107], v[144:147], v[26:29]
	v_mfma_f32_16x16x32_bf16 v[30:33], v[112:115], v[144:147], v[30:33]
	v_mfma_f32_16x16x32_bf16 v[2:5], v[108:111], v[124:127], v[2:5]
	v_mfma_f32_16x16x32_bf16 v[6:9], v[116:119], v[124:127], v[6:9]
	v_mfma_f32_16x16x32_bf16 v[10:13], v[108:111], v[132:135], v[10:13]
	v_mfma_f32_16x16x32_bf16 v[14:17], v[116:119], v[132:135], v[14:17]
	v_mfma_f32_16x16x32_bf16 v[18:21], v[108:111], v[140:143], v[18:21]
	v_mfma_f32_16x16x32_bf16 v[22:25], v[116:119], v[140:143], v[22:25]
	v_mfma_f32_16x16x32_bf16 v[26:29], v[108:111], v[148:151], v[26:29]
	v_mfma_f32_16x16x32_bf16 v[30:33], v[116:119], v[148:151], v[30:33]
	s_setprio 0
	s_barrier
	s_add_i32 m0, s1, 0x1be80
	s_nop 0
	global_load_lds_dwordx4 v[160:161], off offset:384
	s_add_i32 m0, s1, 0x1de80
	s_add_i32 s0, s0, 2
	global_load_lds_dwordx4 v[162:163], off offset:384
	s_waitcnt vmcnt(6)
	s_add_u32 s10, s10, 0x100
	s_addc_u32 s11, s11, 0
	s_cmp_lt_u32 s0, 28
	s_barrier
	s_barrier
	s_cbranch_scc1 .LBB0_108
	s_add_i32 s1, s1, 0x1e000
	s_mov_b64 s[10:11], 0xf80
	v_readfirstlane_b32 s0, v102
	v_lshl_add_u64 v[68:69], v[68:69], 0, s[10:11]
	s_mov_b32 m0, s0
	v_readfirstlane_b32 s0, v103
	ds_read_b128 v[70:73], v99
	ds_read_b128 v[74:77], v99 offset:1024
	ds_read_b128 v[78:81], v99 offset:2048
	ds_read_b128 v[88:91], v99 offset:3072
	ds_read_b128 v[92:95], v0
	ds_read_b128 v[104:107], v0 offset:1024
	ds_read_b128 v[108:111], v0 offset:2048
	ds_read_b128 v[112:115], v0 offset:3072
	ds_read_b128 v[116:119], v0 offset:4096
	ds_read_b128 v[120:123], v0 offset:5120
	ds_read_b128 v[124:127], v0 offset:6144
	ds_read_b128 v[128:131], v0 offset:7168
	global_load_lds_dwordx4 v[68:69], off
	v_lshl_add_u64 v[66:67], v[66:67], 0, s[10:11]
	s_mov_b32 m0, s0
	s_nop 0
	global_load_lds_dwordx4 v[66:67], off
	s_barrier
	s_waitcnt lgkmcnt(0)
	s_setprio 1
	s_waitcnt lgkmcnt(0)
	v_mfma_f32_16x16x32_bf16 v[62:65], v[70:73], v[92:95], v[62:65]
	v_mfma_f32_16x16x32_bf16 v[58:61], v[78:81], v[92:95], v[58:61]
	v_mfma_f32_16x16x32_bf16 v[54:57], v[70:73], v[108:111], v[54:57]
	v_mfma_f32_16x16x32_bf16 v[50:53], v[78:81], v[108:111], v[50:53]
	v_mfma_f32_16x16x32_bf16 v[46:49], v[70:73], v[116:119], v[46:49]
	v_mfma_f32_16x16x32_bf16 v[42:45], v[78:81], v[116:119], v[42:45]
	v_mfma_f32_16x16x32_bf16 v[38:41], v[70:73], v[124:127], v[38:41]
	v_mfma_f32_16x16x32_bf16 v[34:37], v[78:81], v[124:127], v[34:37]
	v_mfma_f32_16x16x32_bf16 v[62:65], v[74:77], v[104:107], v[62:65]
	v_mfma_f32_16x16x32_bf16 v[58:61], v[88:91], v[104:107], v[58:61]
	v_mfma_f32_16x16x32_bf16 v[54:57], v[74:77], v[112:115], v[54:57]
	v_mfma_f32_16x16x32_bf16 v[50:53], v[88:91], v[112:115], v[50:53]
	v_mfma_f32_16x16x32_bf16 v[46:49], v[74:77], v[120:123], v[46:49]
	v_mfma_f32_16x16x32_bf16 v[42:45], v[88:91], v[120:123], v[42:45]
	v_mfma_f32_16x16x32_bf16 v[38:41], v[74:77], v[128:131], v[38:41]
	v_mfma_f32_16x16x32_bf16 v[34:37], v[88:91], v[128:131], v[34:37]
	s_setprio 0
	s_barrier
	s_barrier
	s_waitcnt lgkmcnt(0)
	s_barrier
	ds_read_b128 v[66:69], v0 offset:16384
	ds_read_b128 v[92:95], v0 offset:17408
	ds_read_b128 v[100:103], v0 offset:18432
	ds_read_b128 v[104:107], v0 offset:19456
	ds_read_b128 v[108:111], v0 offset:20480
	ds_read_b128 v[112:115], v0 offset:21504
	ds_read_b128 v[116:119], v0 offset:22528
	ds_read_b128 v[120:123], v0 offset:23552
	s_waitcnt vmcnt(4)
	s_barrier
	s_waitcnt lgkmcnt(0)
	s_setprio 1
	s_waitcnt lgkmcnt(3)
	v_mfma_f32_16x16x32_bf16 v[18:21], v[70:73], v[108:111], v[18:21]
	v_mfma_f32_16x16x32_bf16 v[2:5], v[70:73], v[66:69], v[2:5]
	v_mfma_f32_16x16x32_bf16 v[6:9], v[78:81], v[66:69], v[6:9]
	s_waitcnt lgkmcnt(2)
	v_mfma_f32_16x16x32_bf16 v[66:69], v[74:77], v[112:115], v[18:21]
	v_mfma_f32_16x16x32_bf16 v[18:21], v[78:81], v[108:111], v[22:25]
	v_mfma_f32_16x16x32_bf16 v[2:5], v[74:77], v[92:95], v[2:5]
	v_mfma_f32_16x16x32_bf16 v[6:9], v[88:91], v[92:95], v[6:9]
	v_mfma_f32_16x16x32_bf16 v[10:13], v[70:73], v[100:103], v[10:13]
	v_mfma_f32_16x16x32_bf16 v[14:17], v[78:81], v[100:103], v[14:17]
	v_mfma_f32_16x16x32_bf16 v[92:95], v[88:91], v[112:115], v[18:21]
	s_waitcnt lgkmcnt(1)
	v_mfma_f32_16x16x32_bf16 v[18:21], v[70:73], v[116:119], v[26:29]
	v_mfma_f32_16x16x32_bf16 v[10:13], v[74:77], v[104:107], v[10:13]
	v_mfma_f32_16x16x32_bf16 v[14:17], v[88:91], v[104:107], v[14:17]
	s_waitcnt lgkmcnt(0)
	v_mfma_f32_16x16x32_bf16 v[70:73], v[74:77], v[120:123], v[18:21]
	v_mfma_f32_16x16x32_bf16 v[18:21], v[78:81], v[116:119], v[30:33]
	v_mfma_f32_16x16x32_bf16 v[74:77], v[88:91], v[120:123], v[18:21]
	s_setprio 0
	s_barrier
	ds_read_b128 v[78:81], v99 offset:32768
	ds_read_b128 v[88:91], v99 offset:33792
	ds_read_b128 v[100:103], v99 offset:34816
	ds_read_b128 v[96:99], v99 offset:35840
	s_nop 0
	ds_read_b128 v[18:21], v0 offset:32768
	ds_read_b128 v[22:25], v0 offset:33792
	ds_read_b128 v[26:29], v0 offset:34816
	ds_read_b128 v[30:33], v0 offset:35840
	ds_read_b128 v[104:107], v0 offset:36864
	ds_read_b128 v[108:111], v0 offset:37888
	ds_read_b128 v[112:115], v0 offset:38912
	ds_read_b128 v[116:119], v0 offset:39936
	s_waitcnt vmcnt(2)
	s_barrier
	s_waitcnt lgkmcnt(0)
	s_setprio 1
	s_waitcnt lgkmcnt(7)
	v_mfma_f32_16x16x32_bf16 v[62:65], v[78:81], v[18:21], v[62:65]
	v_mfma_f32_16x16x32_bf16 v[18:21], v[100:103], v[18:21], v[58:61]
	s_waitcnt lgkmcnt(6)
	v_mfma_f32_16x16x32_bf16 v[58:61], v[96:99], v[22:25], v[18:21]
	s_waitcnt lgkmcnt(5)
	v_mfma_f32_16x16x32_bf16 v[18:21], v[78:81], v[26:29], v[54:57]
	s_waitcnt lgkmcnt(4)
	v_mfma_f32_16x16x32_bf16 v[54:57], v[88:91], v[30:33], v[18:21]
	v_mfma_f32_16x16x32_bf16 v[18:21], v[100:103], v[26:29], v[50:53]
	v_mfma_f32_16x16x32_bf16 v[50:53], v[96:99], v[30:33], v[18:21]
	s_waitcnt lgkmcnt(3)
	v_mfma_f32_16x16x32_bf16 v[18:21], v[78:81], v[104:107], v[46:49]
	s_waitcnt lgkmcnt(2)
	v_mfma_f32_16x16x32_bf16 v[46:49], v[88:91], v[108:111], v[18:21]
	v_mfma_f32_16x16x32_bf16 v[18:21], v[100:103], v[104:107], v[42:45]
	v_mfma_f32_16x16x32_bf16 v[42:45], v[96:99], v[108:111], v[18:21]
	s_waitcnt lgkmcnt(1)
	v_mfma_f32_16x16x32_bf16 v[18:21], v[78:81], v[112:115], v[38:41]
	s_waitcnt lgkmcnt(0)
	v_mfma_f32_16x16x32_bf16 v[38:41], v[88:91], v[116:119], v[18:21]
	v_mfma_f32_16x16x32_bf16 v[18:21], v[100:103], v[112:115], v[34:37]
	v_mfma_f32_16x16x32_bf16 v[62:65], v[88:91], v[22:25], v[62:65]
	v_mfma_f32_16x16x32_bf16 v[34:37], v[96:99], v[116:119], v[18:21]
	s_setprio 0
	s_barrier
	s_waitcnt vmcnt(0)
	s_barrier
	s_waitcnt lgkmcnt(0)
	s_barrier
	s_nop 1
	ds_read_b128 v[18:21], v0 offset:49152
	ds_read_b128 v[22:25], v0 offset:50176
	ds_read_b128 v[104:107], v0 offset:51200
	ds_read_b128 v[108:111], v0 offset:52224
	ds_read_b128 v[112:115], v0 offset:53248
	ds_read_b128 v[116:119], v0 offset:54272
	ds_read_b128 v[120:123], v0 offset:55296
	ds_read_b128 v[124:127], v0 offset:56320
	s_barrier
	s_waitcnt lgkmcnt(0)
	s_setprio 1
	s_waitcnt lgkmcnt(7)
	v_mfma_f32_16x16x32_bf16 v[2:5], v[78:81], v[18:21], v[2:5]
	s_waitcnt lgkmcnt(6)
	v_mfma_f32_16x16x32_bf16 v[30:33], v[88:91], v[22:25], v[2:5]
	v_mfma_f32_16x16x32_bf16 v[2:5], v[100:103], v[18:21], v[6:9]
	v_mfma_f32_16x16x32_bf16 v[26:29], v[96:99], v[22:25], v[2:5]
	s_waitcnt lgkmcnt(5)
	v_mfma_f32_16x16x32_bf16 v[2:5], v[78:81], v[104:107], v[10:13]
	s_waitcnt lgkmcnt(4)
	v_mfma_f32_16x16x32_bf16 v[22:25], v[88:91], v[108:111], v[2:5]
	v_mfma_f32_16x16x32_bf16 v[2:5], v[100:103], v[104:107], v[14:17]
	v_mfma_f32_16x16x32_bf16 v[18:21], v[96:99], v[108:111], v[2:5]
	s_waitcnt lgkmcnt(3)
	v_mfma_f32_16x16x32_bf16 v[2:5], v[78:81], v[112:115], v[66:69]
	s_waitcnt lgkmcnt(2)
	v_mfma_f32_16x16x32_bf16 v[14:17], v[88:91], v[116:119], v[2:5]
	v_mfma_f32_16x16x32_bf16 v[2:5], v[100:103], v[112:115], v[92:95]
	v_mfma_f32_16x16x32_bf16 v[10:13], v[96:99], v[116:119], v[2:5]
	s_waitcnt lgkmcnt(1)
	v_mfma_f32_16x16x32_bf16 v[2:5], v[78:81], v[120:123], v[70:73]
	s_waitcnt lgkmcnt(0)
	v_mfma_f32_16x16x32_bf16 v[6:9], v[88:91], v[124:127], v[2:5]
	v_mfma_f32_16x16x32_bf16 v[2:5], v[100:103], v[120:123], v[74:77]
	v_mfma_f32_16x16x32_bf16 v[2:5], v[96:99], v[124:127], v[2:5]
	s_setprio 0
	s_movk_i32 s0, 0x100
	v_cmp_gt_u32_e32 vcc, s0, v82
	s_barrier
	s_and_saveexec_b64 s[0:1], vcc
	s_cbranch_execz .LBB0_111
	s_barrier

.LBB0_688:
	s_or_b64 exec, exec, s[14:15]
	v_mov_b32_e32 v67, v1
	v_add_u32_e32 v94, 0x18000, v85
	v_lshl_add_u64 v[10:11], s[0:1], 0, v[0:1]
	v_lshl_add_u64 v[12:13], s[0:1], 0, v[66:67]
	v_lshl_add_u64 v[14:15], s[10:11], 0, v[0:1]
	v_lshl_add_u64 v[16:17], s[10:11], 0, v[66:67]
	s_mov_b64 s[10:11], 0x80
	v_readfirstlane_b32 s1, v94
	v_add_u32_e32 v96, 0x1a000, v85
	v_lshl_add_u64 v[10:11], v[10:11], 0, s[10:11]
	s_mov_b32 m0, s1
	v_readfirstlane_b32 s1, v96
	v_add_u32_e32 v97, 0x8000, v85
	s_waitcnt vmcnt(4)
	s_barrier
	global_load_lds_dwordx4 v[10:11], off
	v_lshl_add_u64 v[10:11], v[12:13], 0, s[10:11]
	s_mov_b32 m0, s1
	v_readfirstlane_b32 s1, v97
	v_add_u32_e32 v98, 0xa000, v85
	global_load_lds_dwordx4 v[10:11], off
	v_lshl_add_u64 v[10:11], v[14:15], 0, s[10:11]
	s_mov_b32 m0, s1
	v_readfirstlane_b32 s1, v98
	v_add_u32_e32 v99, 0x1c000, v85
	v_lshl_add_u64 v[18:19], s[12:13], 0, v[0:1]
	global_load_lds_dwordx4 v[10:11], off
	v_lshl_add_u64 v[10:11], v[16:17], 0, s[10:11]
	s_mov_b32 m0, s1
	v_readfirstlane_b32 s1, v99
	v_add_u32_e32 v100, 0x1e000, v85
	v_lshl_add_u64 v[20:21], s[12:13], 0, v[66:67]
	global_load_lds_dwordx4 v[10:11], off
	v_lshl_add_u64 v[10:11], v[18:19], 0, s[10:11]
	s_mov_b32 m0, s1
	v_readfirstlane_b32 s1, v100
	global_load_lds_dwordx4 v[10:11], off
	v_lshl_add_u64 v[10:11], v[20:21], 0, s[10:11]
	s_mov_b32 m0, s1
	s_sub_i32 s10, s62, s54
	global_load_lds_dwordx4 v[10:11], off
	s_sub_i32 s10, s10, s64
	s_sext_i32_i16 s10, s10
	s_lshl_b32 s1, s63, 10
	s_lshl_b32 s10, s10, 8
	s_movk_i32 s14, 0x1600
	s_and_b32 s0, s52, 0x80
	s_add_i32 s1, s1, s10
	v_lshrrev_b32_e32 v10, 1, v2
	v_mul_lo_u32 v2, v4, s14
	s_mov_b32 s11, 0x16000
	s_or_b32 s12, s0, s1
	v_mad_u64_u32 v[10:11], s[0:1], v10, s11, v[2:3]
	s_mul_i32 s13, s12, 0x2c00
	v_or_b32_e32 v2, v10, v3
	s_mul_hi_i32 s10, s12, 0x2c00
	v_add_lshl_u32 v2, v2, v5, 1
	s_add_u32 s0, s16, s13
	v_lshrrev_b32_e32 v5, 1, v6
	v_mul_lo_u32 v4, v8, s14
	s_addc_u32 s1, s17, s10
	v_mad_u64_u32 v[4:5], s[10:11], v5, s11, v[4:5]
	v_or_b32_e32 v4, v4, v7
	v_mov_b32_e32 v3, v1
	v_add_lshl_u32 v4, v4, v9, 1
	v_mov_b32_e32 v5, v1
	v_lshl_add_u64 v[68:69], s[0:1], 0, v[2:3]
	v_lshl_add_u64 v[70:71], s[0:1], 0, v[4:5]
	s_add_u32 s0, s20, s66
	s_addc_u32 s1, s21, s72
	s_addk_i32 s12, 0x80
	s_add_i32 s13, s13, 0x160000
	v_and_b32_e32 v84, 15, v80
	v_bfe_u32 v83, v80, 4, 2
	v_lshlrev_b32_e32 v24, 2, v80
	v_lshl_add_u64 v[72:73], s[0:1], 0, v[2:3]
	v_lshl_add_u64 v[74:75], s[0:1], 0, v[4:5]
	s_mul_hi_i32 s1, s12, 0x2c00
	s_add_u32 s0, s16, s13
	v_bfe_u32 v82, v80, 6, 2
	v_lshlrev_b32_e32 v22, 6, v84
	v_lshlrev_b32_e32 v23, 4, v83
	v_and_b32_e32 v24, 32, v24
	s_waitcnt vmcnt(6)
	s_addc_u32 s1, s17, s1
	v_bitop3_b32 v22, v23, v24, v22 bitop3:0x36
	v_lshlrev_b32_e32 v23, 13, v81
	v_lshl_or_b32 v24, v82, 12, v212
	v_lshl_add_u64 v[76:77], s[0:1], 0, v[2:3]
	v_mov_b32_e32 v2, 0
	v_lshl_add_u64 v[78:79], s[0:1], 0, v[4:5]
	s_mov_b32 s0, -2
	s_mov_b64 s[10:11], 0
	v_add_u32_e32 v95, v24, v22
	v_add_u32_e32 v93, v23, v22
	v_mov_b32_e32 v3, v2
	v_mov_b32_e32 v4, v2
	v_mov_b32_e32 v5, v2
	v_mov_b32_e32 v6, v2
	v_mov_b32_e32 v7, v2
	v_mov_b32_e32 v8, v2
	v_mov_b32_e32 v9, v2
	v_mov_b32_e32 v10, v2
	v_mov_b32_e32 v11, v2
	v_mov_b32_e32 v12, v2
	v_mov_b32_e32 v13, v2
	v_mov_b32_e32 v14, v2
	v_mov_b32_e32 v15, v2
	v_mov_b32_e32 v16, v2
	v_mov_b32_e32 v17, v2
	v_mov_b32_e32 v18, v2
	v_mov_b32_e32 v19, v2
	v_mov_b32_e32 v20, v2
	v_mov_b32_e32 v21, v2
	v_mov_b32_e32 v22, v2
	v_mov_b32_e32 v23, v2
	v_mov_b32_e32 v24, v2
	v_mov_b32_e32 v25, v2
	v_mov_b32_e32 v26, v2
	v_mov_b32_e32 v27, v2
	v_mov_b32_e32 v28, v2
	v_mov_b32_e32 v29, v2
	v_mov_b32_e32 v34, v2
	v_mov_b32_e32 v35, v2
	v_mov_b32_e32 v36, v2
	v_mov_b32_e32 v37, v2
	v_mov_b32_e32 v38, v2
	v_mov_b32_e32 v39, v2
	v_mov_b32_e32 v40, v2
	v_mov_b32_e32 v41, v2
	v_mov_b32_e32 v42, v2
	v_mov_b32_e32 v43, v2
	v_mov_b32_e32 v44, v2
	v_mov_b32_e32 v45, v2
	v_mov_b32_e32 v46, v2
	v_mov_b32_e32 v47, v2
	v_mov_b32_e32 v48, v2
	v_mov_b32_e32 v49, v2
	v_mov_b32_e32 v50, v2
	v_mov_b32_e32 v51, v2
	v_mov_b32_e32 v52, v2
	v_mov_b32_e32 v53, v2
	v_mov_b32_e32 v54, v2
	v_mov_b32_e32 v55, v2
	v_mov_b32_e32 v56, v2
	v_mov_b32_e32 v57, v2
	v_mov_b32_e32 v58, v2
	v_mov_b32_e32 v59, v2
	v_mov_b32_e32 v60, v2
	v_mov_b32_e32 v61, v2
	v_mov_b32_e32 v62, v2
	v_mov_b32_e32 v63, v2
	v_mov_b32_e32 v64, v2
	v_mov_b32_e32 v65, v2
	v_mov_b32_e32 v30, v2
	v_mov_b32_e32 v31, v2
	v_mov_b32_e32 v32, v2
	v_mov_b32_e32 v33, v2
	s_barrier
	v_add_u32_e32 v101, 0xc000, v85
	v_add_u32_e32 v102, 0xe000, v85
	v_readfirstlane_b32 s1, v85
	s_nop 1
.LBB0_689:
	ds_read_b128 v[104:107], v95
	ds_read_b128 v[108:111], v95 offset:1024
	ds_read_b128 v[112:115], v95 offset:2048
	ds_read_b128 v[116:119], v95 offset:3072
	v_lshl_add_u64 v[152:153], v[72:73], 0, s[10:11]
	v_lshl_add_u64 v[164:165], v[152:153], 0, s[34:35]
	s_add_i32 m0, s1, 0xc000
	ds_read_b128 v[120:123], v93
	ds_read_b128 v[124:127], v93 offset:1024
	ds_read_b128 v[128:131], v93 offset:2048
	ds_read_b128 v[132:135], v93 offset:3072
	ds_read_b128 v[136:139], v93 offset:4096
	ds_read_b128 v[140:143], v93 offset:5120
	ds_read_b128 v[144:147], v93 offset:6144
	ds_read_b128 v[148:151], v93 offset:7168
	global_load_lds_dwordx4 v[164:165], off
	v_lshl_add_u64 v[154:155], v[74:75], 0, s[10:11]
	s_add_i32 m0, s1, 0xe000
	v_lshl_add_u64 v[86:87], v[154:155], 0, s[34:35]
	global_load_lds_dwordx4 v[86:87], off
	s_waitcnt lgkmcnt(8)
	s_barrier
	s_waitcnt lgkmcnt(0)
	s_setprio 1
	v_mfma_f32_16x16x32_bf16 v[62:65], v[104:107], v[120:123], v[62:65]
	v_mfma_f32_16x16x32_bf16 v[58:61], v[112:115], v[120:123], v[58:61]
	v_mfma_f32_16x16x32_bf16 v[54:57], v[104:107], v[128:131], v[54:57]
	v_mfma_f32_16x16x32_bf16 v[50:53], v[112:115], v[128:131], v[50:53]
	v_mfma_f32_16x16x32_bf16 v[46:49], v[104:107], v[136:139], v[46:49]
	v_mfma_f32_16x16x32_bf16 v[42:45], v[112:115], v[136:139], v[42:45]
	v_mfma_f32_16x16x32_bf16 v[38:41], v[104:107], v[144:147], v[38:41]
	v_mfma_f32_16x16x32_bf16 v[34:37], v[112:115], v[144:147], v[34:37]
	v_mfma_f32_16x16x32_bf16 v[62:65], v[108:111], v[124:127], v[62:65]
	v_mfma_f32_16x16x32_bf16 v[58:61], v[116:119], v[124:127], v[58:61]
	v_mfma_f32_16x16x32_bf16 v[54:57], v[108:111], v[132:135], v[54:57]
	v_mfma_f32_16x16x32_bf16 v[50:53], v[116:119], v[132:135], v[50:53]
	v_mfma_f32_16x16x32_bf16 v[46:49], v[108:111], v[140:143], v[46:49]
	v_mfma_f32_16x16x32_bf16 v[42:45], v[116:119], v[140:143], v[42:45]
	v_mfma_f32_16x16x32_bf16 v[38:41], v[108:111], v[148:151], v[38:41]
	v_mfma_f32_16x16x32_bf16 v[34:37], v[116:119], v[148:151], v[34:37]
	s_setprio 0
	s_barrier
	v_lshl_add_u64 v[156:157], v[68:69], 0, s[10:11]
	s_add_i32 m0, s1, 0xff00
	s_nop 0
	global_load_lds_dwordx4 v[156:157], off offset:256
	s_add_i32 m0, s1, 0x11f00
	v_lshl_add_u64 v[158:159], v[70:71], 0, s[10:11]
	global_load_lds_dwordx4 v[158:159], off offset:256
	v_lshl_add_u64 v[88:89], v[152:153], 0, s[74:75]
	s_mov_b32 m0, s1
	s_barrier
	s_waitcnt lgkmcnt(0)
	s_barrier
	ds_read_b128 v[120:123], v93 offset:16384
	ds_read_b128 v[124:127], v93 offset:17408
	ds_read_b128 v[128:131], v93 offset:18432
	ds_read_b128 v[132:135], v93 offset:19456
	ds_read_b128 v[136:139], v93 offset:20480
	ds_read_b128 v[140:143], v93 offset:21504
	ds_read_b128 v[144:147], v93 offset:22528
	ds_read_b128 v[148:151], v93 offset:23552
	global_load_lds_dwordx4 v[88:89], off
	s_add_i32 m0, s1, 0x1f00
	s_nop 0
	global_load_lds_dwordx4 v[154:155], off offset:256
	s_barrier
	s_waitcnt lgkmcnt(0)
	s_setprio 1
	v_mfma_f32_16x16x32_bf16 v[2:5], v[104:107], v[120:123], v[2:5]
	v_mfma_f32_16x16x32_bf16 v[6:9], v[112:115], v[120:123], v[6:9]
	v_mfma_f32_16x16x32_bf16 v[10:13], v[104:107], v[128:131], v[10:13]
	v_mfma_f32_16x16x32_bf16 v[14:17], v[112:115], v[128:131], v[14:17]
	v_mfma_f32_16x16x32_bf16 v[18:21], v[104:107], v[136:139], v[18:21]
	v_mfma_f32_16x16x32_bf16 v[22:25], v[112:115], v[136:139], v[22:25]
	v_mfma_f32_16x16x32_bf16 v[26:29], v[104:107], v[144:147], v[26:29]
	v_mfma_f32_16x16x32_bf16 v[30:33], v[112:115], v[144:147], v[30:33]
	v_mfma_f32_16x16x32_bf16 v[2:5], v[108:111], v[124:127], v[2:5]
	v_mfma_f32_16x16x32_bf16 v[6:9], v[116:119], v[124:127], v[6:9]
	v_mfma_f32_16x16x32_bf16 v[10:13], v[108:111], v[132:135], v[10:13]
	v_mfma_f32_16x16x32_bf16 v[14:17], v[116:119], v[132:135], v[14:17]
	v_mfma_f32_16x16x32_bf16 v[18:21], v[108:111], v[140:143], v[18:21]
	v_mfma_f32_16x16x32_bf16 v[22:25], v[116:119], v[140:143], v[22:25]
	v_mfma_f32_16x16x32_bf16 v[26:29], v[108:111], v[148:151], v[26:29]
	v_mfma_f32_16x16x32_bf16 v[30:33], v[116:119], v[148:151], v[30:33]
	s_setprio 0
	s_barrier
	v_lshl_add_u64 v[160:161], v[76:77], 0, s[10:11]
	s_add_i32 m0, s1, 0x13f00
	s_nop 0
	global_load_lds_dwordx4 v[160:161], off offset:256
	s_add_i32 m0, s1, 0x15f00
	v_lshl_add_u64 v[162:163], v[78:79], 0, s[10:11]
	global_load_lds_dwordx4 v[162:163], off offset:256
	s_waitcnt vmcnt(6)
	s_barrier
	s_barrier
	ds_read_b128 v[104:107], v95 offset:32768
	ds_read_b128 v[108:111], v95 offset:33792
	ds_read_b128 v[112:115], v95 offset:34816
	ds_read_b128 v[116:119], v95 offset:35840
	s_add_i32 m0, s1, 0x3f80
	ds_read_b128 v[120:123], v93 offset:32768
	ds_read_b128 v[124:127], v93 offset:33792
	ds_read_b128 v[128:131], v93 offset:34816
	ds_read_b128 v[132:135], v93 offset:35840
	ds_read_b128 v[136:139], v93 offset:36864
	ds_read_b128 v[140:143], v93 offset:37888
	ds_read_b128 v[144:147], v93 offset:38912
	ds_read_b128 v[148:151], v93 offset:39936
	global_load_lds_dwordx4 v[164:165], off offset:128
	s_add_i32 m0, s1, 0x5f80
	s_nop 0
	global_load_lds_dwordx4 v[86:87], off offset:128
	s_waitcnt lgkmcnt(8)
	s_barrier
	s_waitcnt lgkmcnt(0)
	s_setprio 1
	v_mfma_f32_16x16x32_bf16 v[62:65], v[104:107], v[120:123], v[62:65]
	v_mfma_f32_16x16x32_bf16 v[58:61], v[112:115], v[120:123], v[58:61]
	v_mfma_f32_16x16x32_bf16 v[54:57], v[104:107], v[128:131], v[54:57]
	v_mfma_f32_16x16x32_bf16 v[50:53], v[112:115], v[128:131], v[50:53]
	v_mfma_f32_16x16x32_bf16 v[46:49], v[104:107], v[136:139], v[46:49]
	v_mfma_f32_16x16x32_bf16 v[42:45], v[112:115], v[136:139], v[42:45]
	v_mfma_f32_16x16x32_bf16 v[38:41], v[104:107], v[144:147], v[38:41]
	v_mfma_f32_16x16x32_bf16 v[34:37], v[112:115], v[144:147], v[34:37]
	v_mfma_f32_16x16x32_bf16 v[62:65], v[108:111], v[124:127], v[62:65]
	v_mfma_f32_16x16x32_bf16 v[58:61], v[116:119], v[124:127], v[58:61]
	v_mfma_f32_16x16x32_bf16 v[54:57], v[108:111], v[132:135], v[54:57]
	v_mfma_f32_16x16x32_bf16 v[50:53], v[116:119], v[132:135], v[50:53]
	v_mfma_f32_16x16x32_bf16 v[46:49], v[108:111], v[140:143], v[46:49]
	v_mfma_f32_16x16x32_bf16 v[42:45], v[116:119], v[140:143], v[42:45]
	v_mfma_f32_16x16x32_bf16 v[38:41], v[108:111], v[148:151], v[38:41]
	v_mfma_f32_16x16x32_bf16 v[34:37], v[116:119], v[148:151], v[34:37]
	s_setprio 0
	s_barrier
	s_add_i32 m0, s1, 0x17e80
	s_nop 0
	global_load_lds_dwordx4 v[156:157], off offset:384
	s_add_i32 m0, s1, 0x19e80
	s_nop 0
	global_load_lds_dwordx4 v[158:159], off offset:384
	s_add_i32 m0, s1, 0x7e80
	s_barrier
	s_waitcnt lgkmcnt(0)
	s_barrier
	ds_read_b128 v[120:123], v93 offset:49152
	ds_read_b128 v[124:127], v93 offset:50176
	ds_read_b128 v[128:131], v93 offset:51200
	ds_read_b128 v[132:135], v93 offset:52224
	ds_read_b128 v[136:139], v93 offset:53248
	ds_read_b128 v[140:143], v93 offset:54272
	ds_read_b128 v[144:147], v93 offset:55296
	ds_read_b128 v[148:151], v93 offset:56320
	global_load_lds_dwordx4 v[152:153], off offset:384
	s_add_i32 m0, s1, 0x9e80
	s_nop 0
	global_load_lds_dwordx4 v[154:155], off offset:384
	s_barrier
	s_waitcnt lgkmcnt(0)
	s_setprio 1
	v_mfma_f32_16x16x32_bf16 v[2:5], v[104:107], v[120:123], v[2:5]
	v_mfma_f32_16x16x32_bf16 v[6:9], v[112:115], v[120:123], v[6:9]
	v_mfma_f32_16x16x32_bf16 v[10:13], v[104:107], v[128:131], v[10:13]
	v_mfma_f32_16x16x32_bf16 v[14:17], v[112:115], v[128:131], v[14:17]
	v_mfma_f32_16x16x32_bf16 v[18:21], v[104:107], v[136:139], v[18:21]
	v_mfma_f32_16x16x32_bf16 v[22:25], v[112:115], v[136:139], v[22:25]
	v_mfma_f32_16x16x32_bf16 v[26:29], v[104:107], v[144:147], v[26:29]
	v_mfma_f32_16x16x32_bf16 v[30:33], v[112:115], v[144:147], v[30:33]
	v_mfma_f32_16x16x32_bf16 v[2:5], v[108:111], v[124:127], v[2:5]
	v_mfma_f32_16x16x32_bf16 v[6:9], v[116:119], v[124:127], v[6:9]
	v_mfma_f32_16x16x32_bf16 v[10:13], v[108:111], v[132:135], v[10:13]
	v_mfma_f32_16x16x32_bf16 v[14:17], v[116:119], v[132:135], v[14:17]
	v_mfma_f32_16x16x32_bf16 v[18:21], v[108:111], v[140:143], v[18:21]
	v_mfma_f32_16x16x32_bf16 v[22:25], v[116:119], v[140:143], v[22:25]
	v_mfma_f32_16x16x32_bf16 v[26:29], v[108:111], v[148:151], v[26:29]
	v_mfma_f32_16x16x32_bf16 v[30:33], v[116:119], v[148:151], v[30:33]
	s_setprio 0
	s_barrier
	s_add_i32 m0, s1, 0x1be80
	s_nop 0
	global_load_lds_dwordx4 v[160:161], off offset:384
	s_add_i32 m0, s1, 0x1de80
	s_add_i32 s0, s0, 2
	global_load_lds_dwordx4 v[162:163], off offset:384
	s_waitcnt vmcnt(6)
	s_add_u32 s10, s10, 0x100
	s_addc_u32 s11, s11, 0
	s_cmpk_lt_u32 s0, 0x54
	s_barrier
	s_barrier
	s_cbranch_scc1 .LBB0_689
	s_add_i32 s1, s1, 0x1e000
	s_add_u32 s0, s8, 0x2b80
	s_addc_u32 s1, s9, 0
	v_readfirstlane_b32 s8, v101
	v_lshl_add_u64 v[90:91], s[0:1], 0, v[0:1]
	s_mov_b32 m0, s8
	v_lshl_add_u64 v[66:67], s[0:1], 0, v[66:67]
	v_readfirstlane_b32 s0, v102
	ds_read_b128 v[68:71], v95
	ds_read_b128 v[72:75], v95 offset:1024
	ds_read_b128 v[76:79], v95 offset:2048
	ds_read_b128 v[86:89], v95 offset:3072
	ds_read_b128 v[96:99], v93
	ds_read_b128 v[104:107], v93 offset:1024
	ds_read_b128 v[108:111], v93 offset:2048
	ds_read_b128 v[112:115], v93 offset:3072
	ds_read_b128 v[116:119], v93 offset:4096
	ds_read_b128 v[120:123], v93 offset:5120
	ds_read_b128 v[124:127], v93 offset:6144
	ds_read_b128 v[128:131], v93 offset:7168
	global_load_lds_dwordx4 v[90:91], off
	s_mov_b32 m0, s0
	s_nop 0
	global_load_lds_dwordx4 v[66:67], off
	s_barrier
	s_waitcnt lgkmcnt(0)
	s_setprio 1
	s_waitcnt lgkmcnt(0)
	v_mfma_f32_16x16x32_bf16 v[62:65], v[68:71], v[96:99], v[62:65]
	v_mfma_f32_16x16x32_bf16 v[58:61], v[76:79], v[96:99], v[58:61]
	v_mfma_f32_16x16x32_bf16 v[54:57], v[68:71], v[108:111], v[54:57]
	v_mfma_f32_16x16x32_bf16 v[50:53], v[76:79], v[108:111], v[50:53]
	v_mfma_f32_16x16x32_bf16 v[46:49], v[68:71], v[116:119], v[46:49]
	v_mfma_f32_16x16x32_bf16 v[42:45], v[76:79], v[116:119], v[42:45]
	v_mfma_f32_16x16x32_bf16 v[38:41], v[68:71], v[124:127], v[38:41]
	v_mfma_f32_16x16x32_bf16 v[34:37], v[76:79], v[124:127], v[34:37]
	v_mfma_f32_16x16x32_bf16 v[62:65], v[72:75], v[104:107], v[62:65]
	v_mfma_f32_16x16x32_bf16 v[58:61], v[86:89], v[104:107], v[58:61]
	v_mfma_f32_16x16x32_bf16 v[54:57], v[72:75], v[112:115], v[54:57]
	v_mfma_f32_16x16x32_bf16 v[50:53], v[86:89], v[112:115], v[50:53]
	v_mfma_f32_16x16x32_bf16 v[46:49], v[72:75], v[120:123], v[46:49]
	v_mfma_f32_16x16x32_bf16 v[42:45], v[86:89], v[120:123], v[42:45]
	v_mfma_f32_16x16x32_bf16 v[38:41], v[72:75], v[128:131], v[38:41]
	v_mfma_f32_16x16x32_bf16 v[34:37], v[86:89], v[128:131], v[34:37]
	s_setprio 0
	s_barrier
	s_barrier
	s_waitcnt lgkmcnt(0)
	s_barrier
	ds_read_b128 v[96:99], v93 offset:16384
	ds_read_b128 v[100:103], v93 offset:17408
	ds_read_b128 v[104:107], v93 offset:18432
	ds_read_b128 v[108:111], v93 offset:19456
	ds_read_b128 v[112:115], v93 offset:20480
	ds_read_b128 v[116:119], v93 offset:21504
	ds_read_b128 v[120:123], v93 offset:22528
	ds_read_b128 v[124:127], v93 offset:23552
	s_waitcnt vmcnt(4)
	s_barrier
	s_waitcnt lgkmcnt(0)
	s_setprio 1
	s_waitcnt lgkmcnt(3)
	v_mfma_f32_16x16x32_bf16 v[18:21], v[68:71], v[112:115], v[18:21]
	v_mfma_f32_16x16x32_bf16 v[2:5], v[68:71], v[96:99], v[2:5]
	v_mfma_f32_16x16x32_bf16 v[6:9], v[76:79], v[96:99], v[6:9]
	s_waitcnt lgkmcnt(2)
	v_mfma_f32_16x16x32_bf16 v[96:99], v[72:75], v[116:119], v[18:21]
	v_mfma_f32_16x16x32_bf16 v[18:21], v[76:79], v[112:115], v[22:25]
	v_mfma_f32_16x16x32_bf16 v[2:5], v[72:75], v[100:103], v[2:5]
	v_mfma_f32_16x16x32_bf16 v[6:9], v[86:89], v[100:103], v[6:9]
	v_mfma_f32_16x16x32_bf16 v[10:13], v[68:71], v[104:107], v[10:13]
	v_mfma_f32_16x16x32_bf16 v[14:17], v[76:79], v[104:107], v[14:17]
	v_mfma_f32_16x16x32_bf16 v[100:103], v[86:89], v[116:119], v[18:21]
	s_waitcnt lgkmcnt(1)
	v_mfma_f32_16x16x32_bf16 v[18:21], v[68:71], v[120:123], v[26:29]
	v_mfma_f32_16x16x32_bf16 v[10:13], v[72:75], v[108:111], v[10:13]
	v_mfma_f32_16x16x32_bf16 v[14:17], v[86:89], v[108:111], v[14:17]
	s_waitcnt lgkmcnt(0)
	v_mfma_f32_16x16x32_bf16 v[66:69], v[72:75], v[124:127], v[18:21]
	v_mfma_f32_16x16x32_bf16 v[18:21], v[76:79], v[120:123], v[30:33]
	v_mfma_f32_16x16x32_bf16 v[70:73], v[86:89], v[124:127], v[18:21]
	s_setprio 0
	s_barrier
	ds_read_b128 v[74:77], v95 offset:32768
	ds_read_b128 v[86:89], v95 offset:33792
	ds_read_b128 v[104:107], v95 offset:34816
	ds_read_b128 v[108:111], v95 offset:35840
	s_nop 0
	ds_read_b128 v[18:21], v93 offset:32768
	ds_read_b128 v[22:25], v93 offset:33792
	ds_read_b128 v[26:29], v93 offset:34816
	ds_read_b128 v[30:33], v93 offset:35840
	ds_read_b128 v[112:115], v93 offset:36864
	ds_read_b128 v[116:119], v93 offset:37888
	ds_read_b128 v[120:123], v93 offset:38912
	ds_read_b128 v[124:127], v93 offset:39936
	s_waitcnt vmcnt(2)
	s_barrier
	s_waitcnt lgkmcnt(0)
	s_setprio 1
	s_waitcnt lgkmcnt(7)
	v_mfma_f32_16x16x32_bf16 v[62:65], v[74:77], v[18:21], v[62:65]
	v_mfma_f32_16x16x32_bf16 v[18:21], v[104:107], v[18:21], v[58:61]
	s_waitcnt lgkmcnt(6)
	v_mfma_f32_16x16x32_bf16 v[58:61], v[108:111], v[22:25], v[18:21]
	s_waitcnt lgkmcnt(5)
	v_mfma_f32_16x16x32_bf16 v[18:21], v[74:77], v[26:29], v[54:57]
	s_waitcnt lgkmcnt(4)
	v_mfma_f32_16x16x32_bf16 v[54:57], v[86:89], v[30:33], v[18:21]
	v_mfma_f32_16x16x32_bf16 v[18:21], v[104:107], v[26:29], v[50:53]
	v_mfma_f32_16x16x32_bf16 v[50:53], v[108:111], v[30:33], v[18:21]
	s_waitcnt lgkmcnt(3)
	v_mfma_f32_16x16x32_bf16 v[18:21], v[74:77], v[112:115], v[46:49]
	s_waitcnt lgkmcnt(2)
	v_mfma_f32_16x16x32_bf16 v[46:49], v[86:89], v[116:119], v[18:21]
	v_mfma_f32_16x16x32_bf16 v[18:21], v[104:107], v[112:115], v[42:45]
	v_mfma_f32_16x16x32_bf16 v[42:45], v[108:111], v[116:119], v[18:21]
	s_waitcnt lgkmcnt(1)
	v_mfma_f32_16x16x32_bf16 v[18:21], v[74:77], v[120:123], v[38:41]
	s_waitcnt lgkmcnt(0)
	v_mfma_f32_16x16x32_bf16 v[38:41], v[86:89], v[124:127], v[18:21]
	v_mfma_f32_16x16x32_bf16 v[18:21], v[104:107], v[120:123], v[34:37]
	v_mfma_f32_16x16x32_bf16 v[62:65], v[86:89], v[22:25], v[62:65]
	v_mfma_f32_16x16x32_bf16 v[34:37], v[108:111], v[124:127], v[18:21]
	s_setprio 0
	s_barrier
	s_waitcnt vmcnt(0)
	s_barrier
	s_waitcnt lgkmcnt(0)
	s_barrier
	s_nop 1
	ds_read_b128 v[18:21], v93 offset:49152
	ds_read_b128 v[22:25], v93 offset:50176
	ds_read_b128 v[112:115], v93 offset:51200
	ds_read_b128 v[116:119], v93 offset:52224
	ds_read_b128 v[120:123], v93 offset:53248
	ds_read_b128 v[124:127], v93 offset:54272
	ds_read_b128 v[128:131], v93 offset:55296
	ds_read_b128 v[90:93], v93 offset:56320
	s_barrier
	s_waitcnt lgkmcnt(0)
	s_setprio 1
	s_waitcnt lgkmcnt(7)
	v_mfma_f32_16x16x32_bf16 v[2:5], v[74:77], v[18:21], v[2:5]
	s_waitcnt lgkmcnt(6)
	v_mfma_f32_16x16x32_bf16 v[30:33], v[86:89], v[22:25], v[2:5]
	v_mfma_f32_16x16x32_bf16 v[2:5], v[104:107], v[18:21], v[6:9]
	v_mfma_f32_16x16x32_bf16 v[26:29], v[108:111], v[22:25], v[2:5]
	s_waitcnt lgkmcnt(5)
	v_mfma_f32_16x16x32_bf16 v[2:5], v[74:77], v[112:115], v[10:13]
	s_waitcnt lgkmcnt(4)
	v_mfma_f32_16x16x32_bf16 v[22:25], v[86:89], v[116:119], v[2:5]
	v_mfma_f32_16x16x32_bf16 v[2:5], v[104:107], v[112:115], v[14:17]
	v_mfma_f32_16x16x32_bf16 v[18:21], v[108:111], v[116:119], v[2:5]
	s_waitcnt lgkmcnt(3)
	v_mfma_f32_16x16x32_bf16 v[2:5], v[74:77], v[120:123], v[96:99]
	s_waitcnt lgkmcnt(2)
	v_mfma_f32_16x16x32_bf16 v[14:17], v[86:89], v[124:127], v[2:5]
	v_mfma_f32_16x16x32_bf16 v[2:5], v[104:107], v[120:123], v[100:103]
	v_mfma_f32_16x16x32_bf16 v[10:13], v[108:111], v[124:127], v[2:5]
	s_waitcnt lgkmcnt(1)
	v_mfma_f32_16x16x32_bf16 v[2:5], v[74:77], v[128:131], v[66:69]
	s_waitcnt lgkmcnt(0)
	v_mfma_f32_16x16x32_bf16 v[6:9], v[86:89], v[90:93], v[2:5]
	v_mfma_f32_16x16x32_bf16 v[2:5], v[104:107], v[128:131], v[70:73]
	v_mfma_f32_16x16x32_bf16 v[2:5], v[108:111], v[90:93], v[2:5]
	s_setprio 0
	s_movk_i32 s0, 0x100
	v_cmp_gt_u32_e32 vcc, s0, v80
	s_barrier
	s_and_saveexec_b64 s[0:1], vcc
	s_cbranch_execz .LBB0_692
	s_barrier
